# v113 + G1 gate-code segment stores write-through (sc1) instead of nt
# speedup vs baseline: 1.0263x; 1.0263x over previous
.LBB0_264:
	s_and_b64 vcc, exec, s[4:5]
	s_cbranch_vccz .LBB0_266
	v_pk_mul_f32 v[128:129], v[126:127], s[60:61] op_sel_hi:[1,0]
	v_pk_mul_f32 v[132:133], v[124:125], s[60:61] op_sel_hi:[1,0]
	v_exp_f32_e32 v128, v128
	v_exp_f32_e32 v132, v132
	v_exp_f32_e32 v133, v133
	v_exp_f32_e32 v129, v129
	v_pk_mul_f32 v[156:157], v[120:121], s[60:61] op_sel_hi:[1,0]
	s_lshl_b32 s4, s14, 2
	v_pk_add_f32 v[132:133], v[132:133], 1.0 op_sel_hi:[1,0]
	v_pk_add_f32 v[128:129], v[128:129], 1.0 op_sel_hi:[1,0]
	v_rcp_f32_e32 v132, v132
	v_rcp_f32_e32 v133, v133
	v_rcp_f32_e32 v134, v128
	v_rcp_f32_e32 v135, v129
	v_exp_f32_e32 v156, v156
	v_exp_f32_e32 v157, v157
	s_or_b32 s4, s4, s18
	s_mov_b32 s18, 0x4b000000
	v_mov_b64_e32 v[128:129], s[18:19]
	v_pk_fma_f32 v[134:135], v[134:135], s[62:63], v[128:129] op_sel_hi:[1,0,0]
	v_pk_fma_f32 v[132:133], v[132:133], s[62:63], v[128:129] op_sel_hi:[1,0,0]
	v_pk_add_f32 v[156:157], v[156:157], 1.0 op_sel_hi:[1,0]
	v_max_f32_e32 v132, 0x4b000001, v132
	v_max_f32_e32 v133, 0x4b000001, v133
	v_max_f32_e32 v134, 0x4b000001, v134
	v_max_f32_e32 v135, 0x4b000001, v135
	v_rcp_f32_e32 v156, v156
	v_rcp_f32_e32 v157, v157
	v_perm_b32 v132, v133, v132, s46
	v_perm_b32 v133, v135, v134, s46
	v_pk_mul_f32 v[134:135], v[122:123], s[60:61] op_sel_hi:[1,0]
	v_pk_fma_f32 v[156:157], v[156:157], s[62:63], v[128:129] op_sel_hi:[1,0,0]
	v_exp_f32_e32 v134, v134
	v_exp_f32_e32 v135, v135
	v_perm_b32 v132, v133, v132, s47
	v_max_f32_e32 v133, 0x4b000001, v156
	v_max_f32_e32 v151, 0x4b000001, v157
	v_pk_mul_f32 v[156:157], v[116:117], s[60:61] op_sel_hi:[1,0]
	v_pk_add_f32 v[134:135], v[134:135], 1.0 op_sel_hi:[1,0]
	v_exp_f32_e32 v156, v156
	v_exp_f32_e32 v157, v157
	v_rcp_f32_e32 v134, v134
	v_rcp_f32_e32 v135, v135
	v_perm_b32 v133, v151, v133, s46
	v_pk_add_f32 v[156:157], v[156:157], 1.0 op_sel_hi:[1,0]
	v_pk_mul_f32 v[158:159], v[112:113], s[60:61] op_sel_hi:[1,0]
	v_pk_fma_f32 v[134:135], v[134:135], s[62:63], v[128:129] op_sel_hi:[1,0,0]
	v_rcp_f32_e32 v156, v156
	v_rcp_f32_e32 v157, v157
	v_max_f32_e32 v134, 0x4b000001, v134
	v_max_f32_e32 v135, 0x4b000001, v135
	v_perm_b32 v134, v135, v134, s46
	v_perm_b32 v133, v134, v133, s47
	v_pk_mul_f32 v[134:135], v[118:119], s[60:61] op_sel_hi:[1,0]
	v_pk_fma_f32 v[156:157], v[156:157], s[62:63], v[128:129] op_sel_hi:[1,0,0]
	v_exp_f32_e32 v134, v134
	v_exp_f32_e32 v135, v135
	v_max_f32_e32 v151, 0x4b000001, v156
	v_max_f32_e32 v153, 0x4b000001, v157
	v_pk_mul_f32 v[156:157], v[114:115], s[60:61] op_sel_hi:[1,0]
	v_exp_f32_e32 v158, v158
	v_exp_f32_e32 v159, v159
	v_exp_f32_e32 v156, v156
	v_exp_f32_e32 v157, v157
	v_pk_add_f32 v[134:135], v[134:135], 1.0 op_sel_hi:[1,0]
	v_pk_add_f32 v[158:159], v[158:159], 1.0 op_sel_hi:[1,0]
	v_rcp_f32_e32 v134, v134
	v_rcp_f32_e32 v135, v135
	v_pk_add_f32 v[156:157], v[156:157], 1.0 op_sel_hi:[1,0]
	v_rcp_f32_e32 v158, v158
	v_rcp_f32_e32 v159, v159
	v_rcp_f32_e32 v156, v156
	v_rcp_f32_e32 v157, v157
	v_pk_fma_f32 v[134:135], v[134:135], s[62:63], v[128:129] op_sel_hi:[1,0,0]
	s_ashr_i32 s5, s4, 31
	v_max_f32_e32 v134, 0x4b000001, v134
	v_max_f32_e32 v135, 0x4b000001, v135
	v_perm_b32 v151, v153, v151, s46
	v_perm_b32 v134, v135, v134, s46
	v_pk_fma_f32 v[156:157], v[156:157], s[62:63], v[128:129] op_sel_hi:[1,0,0]
	v_pk_fma_f32 v[158:159], v[158:159], s[62:63], v[128:129] op_sel_hi:[1,0,0]
	s_lshl_b64 s[4:5], s[4:5], 16
	v_perm_b32 v134, v134, v151, s47
	v_max_f32_e32 v135, 0x4b000001, v158
	v_max_f32_e32 v151, 0x4b000001, v159
	v_max_f32_e32 v153, 0x4b000001, v156
	v_max_f32_e32 v155, 0x4b000001, v157
	s_add_u32 s4, s72, s4
	v_perm_b32 v135, v151, v135, s46
	v_perm_b32 v151, v155, v153, s46
	s_addc_u32 s5, s73, s5
	v_lshl_add_u32 v144, v185, 4, s90
	v_perm_b32 v135, v151, v135, s47
	global_store_dwordx4 v144, v[132:135], s[4:5] sc1
	v_pk_mul_f32 v[156:157], v[104:105], s[60:61] op_sel_hi:[1,0]
	v_pk_mul_f32 v[158:159], v[96:97], s[60:61] op_sel_hi:[1,0]
	v_pk_mul_f32 v[132:133], v[110:111], s[60:61] op_sel_hi:[1,0]
	v_pk_mul_f32 v[134:135], v[108:109], s[60:61] op_sel_hi:[1,0]
	v_exp_f32_e32 v132, v132
	v_exp_f32_e32 v134, v134
	v_exp_f32_e32 v135, v135
	v_exp_f32_e32 v133, v133
	v_exp_f32_e32 v156, v156
	v_exp_f32_e32 v157, v157
	v_pk_add_f32 v[134:135], v[134:135], 1.0 op_sel_hi:[1,0]
	v_pk_add_f32 v[132:133], v[132:133], 1.0 op_sel_hi:[1,0]
	v_rcp_f32_e32 v134, v134
	v_rcp_f32_e32 v135, v135
	v_rcp_f32_e32 v132, v132
	v_rcp_f32_e32 v133, v133
	v_pk_add_f32 v[156:157], v[156:157], 1.0 op_sel_hi:[1,0]
	v_pk_fma_f32 v[134:135], v[134:135], s[62:63], v[128:129] op_sel_hi:[1,0,0]
	v_rcp_f32_e32 v156, v156
	v_pk_fma_f32 v[132:133], v[132:133], s[62:63], v[128:129] op_sel_hi:[1,0,0]
	v_max_f32_e32 v134, 0x4b000001, v134
	v_max_f32_e32 v135, 0x4b000001, v135
	v_max_f32_e32 v132, 0x4b000001, v132
	v_max_f32_e32 v133, 0x4b000001, v133
	v_perm_b32 v134, v135, v134, s46
	v_perm_b32 v132, v133, v132, s46
	v_rcp_f32_e32 v157, v157
	v_perm_b32 v132, v132, v134, s47
	v_pk_mul_f32 v[134:135], v[106:107], s[60:61] op_sel_hi:[1,0]
	v_exp_f32_e32 v158, v158
	v_exp_f32_e32 v134, v134
	v_exp_f32_e32 v135, v135
	v_pk_fma_f32 v[156:157], v[156:157], s[62:63], v[128:129] op_sel_hi:[1,0,0]
	v_exp_f32_e32 v159, v159
	v_max_f32_e32 v133, 0x4b000001, v156
	v_max_f32_e32 v151, 0x4b000001, v157
	v_pk_mul_f32 v[156:157], v[100:101], s[60:61] op_sel_hi:[1,0]
	v_pk_add_f32 v[134:135], v[134:135], 1.0 op_sel_hi:[1,0]
	v_exp_f32_e32 v156, v156
	v_exp_f32_e32 v157, v157
	v_rcp_f32_e32 v134, v134
	v_rcp_f32_e32 v135, v135
	v_perm_b32 v133, v151, v133, s46
	v_pk_add_f32 v[156:157], v[156:157], 1.0 op_sel_hi:[1,0]
	v_pk_add_f32 v[158:159], v[158:159], 1.0 op_sel_hi:[1,0]
	v_pk_fma_f32 v[134:135], v[134:135], s[62:63], v[128:129] op_sel_hi:[1,0,0]
	v_rcp_f32_e32 v156, v156
	v_rcp_f32_e32 v157, v157
	v_max_f32_e32 v134, 0x4b000001, v134
	v_max_f32_e32 v135, 0x4b000001, v135
	v_perm_b32 v134, v135, v134, s46
	v_perm_b32 v133, v134, v133, s47
	v_pk_mul_f32 v[134:135], v[102:103], s[60:61] op_sel_hi:[1,0]
	v_pk_fma_f32 v[156:157], v[156:157], s[62:63], v[128:129] op_sel_hi:[1,0,0]
	v_exp_f32_e32 v134, v134
	v_exp_f32_e32 v135, v135
	v_max_f32_e32 v151, 0x4b000001, v156
	v_max_f32_e32 v153, 0x4b000001, v157
	v_pk_mul_f32 v[156:157], v[98:99], s[60:61] op_sel_hi:[1,0]
	v_pk_add_f32 v[134:135], v[134:135], 1.0 op_sel_hi:[1,0]
	v_exp_f32_e32 v156, v156
	v_exp_f32_e32 v157, v157
	v_rcp_f32_e32 v134, v134
	v_rcp_f32_e32 v135, v135
	v_rcp_f32_e32 v158, v158
	v_pk_add_f32 v[156:157], v[156:157], 1.0 op_sel_hi:[1,0]
	v_rcp_f32_e32 v159, v159
	v_rcp_f32_e32 v156, v156
	v_rcp_f32_e32 v157, v157
	v_pk_fma_f32 v[134:135], v[134:135], s[62:63], v[128:129] op_sel_hi:[1,0,0]
	v_perm_b32 v151, v153, v151, s46
	v_max_f32_e32 v134, 0x4b000001, v134
	v_max_f32_e32 v135, 0x4b000001, v135
	v_perm_b32 v134, v135, v134, s46
	v_pk_fma_f32 v[156:157], v[156:157], s[62:63], v[128:129] op_sel_hi:[1,0,0]
	v_pk_fma_f32 v[158:159], v[158:159], s[62:63], v[128:129] op_sel_hi:[1,0,0]
	v_perm_b32 v134, v134, v151, s47
	v_max_f32_e32 v135, 0x4b000001, v158
	v_max_f32_e32 v151, 0x4b000001, v159
	v_max_f32_e32 v153, 0x4b000001, v156
	v_max_f32_e32 v155, 0x4b000001, v157
	v_perm_b32 v135, v151, v135, s46
	v_perm_b32 v151, v155, v153, s46
	v_perm_b32 v135, v151, v135, s47
	global_store_dwordx4 v144, v[132:135], s[4:5] offset:1024 sc1
	v_pk_mul_f32 v[156:157], v[88:89], s[60:61] op_sel_hi:[1,0]
	v_pk_mul_f32 v[158:159], v[80:81], s[60:61] op_sel_hi:[1,0]
	v_pk_mul_f32 v[132:133], v[94:95], s[60:61] op_sel_hi:[1,0]
	v_pk_mul_f32 v[134:135], v[92:93], s[60:61] op_sel_hi:[1,0]
	v_exp_f32_e32 v132, v132
	v_exp_f32_e32 v134, v134
	v_exp_f32_e32 v135, v135
	v_exp_f32_e32 v133, v133
	v_exp_f32_e32 v156, v156
	v_exp_f32_e32 v157, v157
	v_pk_add_f32 v[134:135], v[134:135], 1.0 op_sel_hi:[1,0]
	v_pk_add_f32 v[132:133], v[132:133], 1.0 op_sel_hi:[1,0]
	v_rcp_f32_e32 v134, v134
	v_rcp_f32_e32 v135, v135
	v_rcp_f32_e32 v132, v132
	v_rcp_f32_e32 v133, v133
	v_pk_add_f32 v[156:157], v[156:157], 1.0 op_sel_hi:[1,0]
	v_pk_fma_f32 v[134:135], v[134:135], s[62:63], v[128:129] op_sel_hi:[1,0,0]
	v_rcp_f32_e32 v156, v156
	v_pk_fma_f32 v[132:133], v[132:133], s[62:63], v[128:129] op_sel_hi:[1,0,0]
	v_max_f32_e32 v134, 0x4b000001, v134
	v_max_f32_e32 v135, 0x4b000001, v135
	v_max_f32_e32 v132, 0x4b000001, v132
	v_max_f32_e32 v133, 0x4b000001, v133
	v_perm_b32 v134, v135, v134, s46
	v_perm_b32 v132, v133, v132, s46
	v_rcp_f32_e32 v157, v157
	v_perm_b32 v132, v132, v134, s47
	v_pk_mul_f32 v[134:135], v[90:91], s[60:61] op_sel_hi:[1,0]
	v_exp_f32_e32 v158, v158
	v_exp_f32_e32 v134, v134
	v_exp_f32_e32 v135, v135
	v_pk_fma_f32 v[156:157], v[156:157], s[62:63], v[128:129] op_sel_hi:[1,0,0]
	v_exp_f32_e32 v159, v159
	v_max_f32_e32 v133, 0x4b000001, v156
	v_max_f32_e32 v151, 0x4b000001, v157
	v_pk_mul_f32 v[156:157], v[84:85], s[60:61] op_sel_hi:[1,0]
	v_pk_add_f32 v[134:135], v[134:135], 1.0 op_sel_hi:[1,0]
	v_exp_f32_e32 v156, v156
	v_exp_f32_e32 v157, v157
	v_rcp_f32_e32 v134, v134
	v_rcp_f32_e32 v135, v135
	v_perm_b32 v133, v151, v133, s46
	v_pk_add_f32 v[156:157], v[156:157], 1.0 op_sel_hi:[1,0]
	v_pk_add_f32 v[158:159], v[158:159], 1.0 op_sel_hi:[1,0]
	v_pk_fma_f32 v[134:135], v[134:135], s[62:63], v[128:129] op_sel_hi:[1,0,0]
	v_rcp_f32_e32 v156, v156
	v_rcp_f32_e32 v157, v157
	v_max_f32_e32 v134, 0x4b000001, v134
	v_max_f32_e32 v135, 0x4b000001, v135
	v_perm_b32 v134, v135, v134, s46
	v_perm_b32 v133, v134, v133, s47
	v_pk_mul_f32 v[134:135], v[86:87], s[60:61] op_sel_hi:[1,0]
	v_pk_fma_f32 v[156:157], v[156:157], s[62:63], v[128:129] op_sel_hi:[1,0,0]
	v_exp_f32_e32 v134, v134
	v_exp_f32_e32 v135, v135
	v_max_f32_e32 v151, 0x4b000001, v156
	v_max_f32_e32 v153, 0x4b000001, v157
	v_pk_mul_f32 v[156:157], v[82:83], s[60:61] op_sel_hi:[1,0]
	v_pk_add_f32 v[134:135], v[134:135], 1.0 op_sel_hi:[1,0]
	v_exp_f32_e32 v156, v156
	v_exp_f32_e32 v157, v157
	v_rcp_f32_e32 v134, v134
	v_rcp_f32_e32 v135, v135
	v_rcp_f32_e32 v158, v158
	v_pk_add_f32 v[156:157], v[156:157], 1.0 op_sel_hi:[1,0]
	v_rcp_f32_e32 v159, v159
	v_rcp_f32_e32 v156, v156
	v_rcp_f32_e32 v157, v157
	v_pk_fma_f32 v[134:135], v[134:135], s[62:63], v[128:129] op_sel_hi:[1,0,0]
	v_perm_b32 v151, v153, v151, s46
	v_max_f32_e32 v134, 0x4b000001, v134
	v_max_f32_e32 v135, 0x4b000001, v135
	v_perm_b32 v134, v135, v134, s46
	v_pk_fma_f32 v[156:157], v[156:157], s[62:63], v[128:129] op_sel_hi:[1,0,0]
	v_pk_fma_f32 v[158:159], v[158:159], s[62:63], v[128:129] op_sel_hi:[1,0,0]
	v_perm_b32 v134, v134, v151, s47
	v_max_f32_e32 v135, 0x4b000001, v158
	v_max_f32_e32 v151, 0x4b000001, v159
	v_max_f32_e32 v153, 0x4b000001, v156
	v_max_f32_e32 v155, 0x4b000001, v157
	v_perm_b32 v135, v151, v135, s46
	v_perm_b32 v151, v155, v153, s46
	v_perm_b32 v135, v151, v135, s47
	global_store_dwordx4 v144, v[132:135], s[4:5] offset:2048 sc1
	v_pk_mul_f32 v[156:157], v[72:73], s[60:61] op_sel_hi:[1,0]
	v_pk_mul_f32 v[158:159], v[64:65], s[60:61] op_sel_hi:[1,0]
	v_pk_mul_f32 v[132:133], v[78:79], s[60:61] op_sel_hi:[1,0]
	v_pk_mul_f32 v[134:135], v[76:77], s[60:61] op_sel_hi:[1,0]
	v_exp_f32_e32 v132, v132
	v_exp_f32_e32 v134, v134
	v_exp_f32_e32 v135, v135
	v_exp_f32_e32 v133, v133
	v_exp_f32_e32 v156, v156
	v_exp_f32_e32 v157, v157
	v_pk_add_f32 v[134:135], v[134:135], 1.0 op_sel_hi:[1,0]
	v_pk_add_f32 v[132:133], v[132:133], 1.0 op_sel_hi:[1,0]
	v_rcp_f32_e32 v134, v134
	v_rcp_f32_e32 v135, v135
	v_rcp_f32_e32 v132, v132
	v_rcp_f32_e32 v133, v133
	v_pk_add_f32 v[156:157], v[156:157], 1.0 op_sel_hi:[1,0]
	v_pk_fma_f32 v[134:135], v[134:135], s[62:63], v[128:129] op_sel_hi:[1,0,0]
	v_rcp_f32_e32 v156, v156
	v_pk_fma_f32 v[132:133], v[132:133], s[62:63], v[128:129] op_sel_hi:[1,0,0]
	v_max_f32_e32 v134, 0x4b000001, v134
	v_max_f32_e32 v135, 0x4b000001, v135
	v_max_f32_e32 v132, 0x4b000001, v132
	v_max_f32_e32 v133, 0x4b000001, v133
	v_perm_b32 v134, v135, v134, s46
	v_perm_b32 v132, v133, v132, s46
	v_rcp_f32_e32 v157, v157
	v_perm_b32 v132, v132, v134, s47
	v_pk_mul_f32 v[134:135], v[74:75], s[60:61] op_sel_hi:[1,0]
	v_exp_f32_e32 v158, v158
	v_exp_f32_e32 v134, v134
	v_exp_f32_e32 v135, v135
	v_pk_fma_f32 v[156:157], v[156:157], s[62:63], v[128:129] op_sel_hi:[1,0,0]
	v_exp_f32_e32 v159, v159
	v_max_f32_e32 v133, 0x4b000001, v156
	v_max_f32_e32 v151, 0x4b000001, v157
	v_pk_mul_f32 v[156:157], v[68:69], s[60:61] op_sel_hi:[1,0]
	v_pk_add_f32 v[134:135], v[134:135], 1.0 op_sel_hi:[1,0]
	v_exp_f32_e32 v156, v156
	v_exp_f32_e32 v157, v157
	v_rcp_f32_e32 v134, v134
	v_rcp_f32_e32 v135, v135
	v_perm_b32 v133, v151, v133, s46
	v_pk_add_f32 v[156:157], v[156:157], 1.0 op_sel_hi:[1,0]
	v_pk_add_f32 v[158:159], v[158:159], 1.0 op_sel_hi:[1,0]
	v_pk_fma_f32 v[134:135], v[134:135], s[62:63], v[128:129] op_sel_hi:[1,0,0]
	v_rcp_f32_e32 v156, v156
	v_rcp_f32_e32 v157, v157
	v_max_f32_e32 v134, 0x4b000001, v134
	v_max_f32_e32 v135, 0x4b000001, v135
	v_perm_b32 v134, v135, v134, s46
	v_perm_b32 v133, v134, v133, s47
	v_pk_mul_f32 v[134:135], v[70:71], s[60:61] op_sel_hi:[1,0]
	v_pk_fma_f32 v[156:157], v[156:157], s[62:63], v[128:129] op_sel_hi:[1,0,0]
	v_exp_f32_e32 v134, v134
	v_exp_f32_e32 v135, v135
	v_max_f32_e32 v151, 0x4b000001, v156
	v_max_f32_e32 v153, 0x4b000001, v157
	v_pk_mul_f32 v[156:157], v[66:67], s[60:61] op_sel_hi:[1,0]
	v_pk_add_f32 v[134:135], v[134:135], 1.0 op_sel_hi:[1,0]
	v_exp_f32_e32 v156, v156
	v_exp_f32_e32 v157, v157
	v_rcp_f32_e32 v134, v134
	v_rcp_f32_e32 v135, v135
	v_rcp_f32_e32 v158, v158
	v_pk_add_f32 v[156:157], v[156:157], 1.0 op_sel_hi:[1,0]
	v_rcp_f32_e32 v159, v159
	v_rcp_f32_e32 v156, v156
	v_rcp_f32_e32 v157, v157
	v_pk_fma_f32 v[134:135], v[134:135], s[62:63], v[128:129] op_sel_hi:[1,0,0]
	v_perm_b32 v151, v153, v151, s46
	v_max_f32_e32 v134, 0x4b000001, v134
	v_max_f32_e32 v135, 0x4b000001, v135
	v_perm_b32 v134, v135, v134, s46
	v_pk_fma_f32 v[156:157], v[156:157], s[62:63], v[128:129] op_sel_hi:[1,0,0]
	v_pk_fma_f32 v[158:159], v[158:159], s[62:63], v[128:129] op_sel_hi:[1,0,0]
	v_perm_b32 v134, v134, v151, s47
	v_max_f32_e32 v135, 0x4b000001, v158
	v_max_f32_e32 v151, 0x4b000001, v159
	v_max_f32_e32 v153, 0x4b000001, v156
	v_max_f32_e32 v155, 0x4b000001, v157
	v_perm_b32 v135, v151, v135, s46
	v_perm_b32 v151, v155, v153, s46
	v_perm_b32 v135, v151, v135, s47
	global_store_dwordx4 v144, v[132:135], s[4:5] offset:3072 sc1
	v_pk_mul_f32 v[156:157], v[56:57], s[60:61] op_sel_hi:[1,0]
	v_lshl_add_u64 v[130:131], s[4:5], 0, v[144:145]
	v_pk_mul_f32 v[132:133], v[62:63], s[60:61] op_sel_hi:[1,0]
	v_pk_mul_f32 v[134:135], v[60:61], s[60:61] op_sel_hi:[1,0]
	v_exp_f32_e32 v132, v132
	v_exp_f32_e32 v134, v134
	v_exp_f32_e32 v135, v135
	v_exp_f32_e32 v133, v133
	v_exp_f32_e32 v156, v156
	v_exp_f32_e32 v157, v157
	v_pk_add_f32 v[134:135], v[134:135], 1.0 op_sel_hi:[1,0]
	v_pk_add_f32 v[132:133], v[132:133], 1.0 op_sel_hi:[1,0]
	v_rcp_f32_e32 v134, v134
	v_rcp_f32_e32 v135, v135
	v_rcp_f32_e32 v132, v132
	v_rcp_f32_e32 v133, v133
	v_pk_add_f32 v[156:157], v[156:157], 1.0 op_sel_hi:[1,0]
	v_pk_fma_f32 v[134:135], v[134:135], s[62:63], v[128:129] op_sel_hi:[1,0,0]
	v_rcp_f32_e32 v156, v156
	v_pk_fma_f32 v[132:133], v[132:133], s[62:63], v[128:129] op_sel_hi:[1,0,0]
	v_max_f32_e32 v134, 0x4b000001, v134
	v_max_f32_e32 v135, 0x4b000001, v135
	v_max_f32_e32 v132, 0x4b000001, v132
	v_max_f32_e32 v133, 0x4b000001, v133
	v_perm_b32 v134, v135, v134, s46
	v_perm_b32 v132, v133, v132, s46
	v_rcp_f32_e32 v157, v157
	v_perm_b32 v132, v132, v134, s47
	v_pk_mul_f32 v[134:135], v[58:59], s[60:61] op_sel_hi:[1,0]
	v_pk_mul_f32 v[158:159], v[48:49], s[60:61] op_sel_hi:[1,0]
	v_exp_f32_e32 v134, v134
	v_exp_f32_e32 v135, v135
	v_pk_fma_f32 v[156:157], v[156:157], s[62:63], v[128:129] op_sel_hi:[1,0,0]
	v_exp_f32_e32 v158, v158
	v_max_f32_e32 v133, 0x4b000001, v156
	v_max_f32_e32 v144, 0x4b000001, v157
	v_pk_mul_f32 v[156:157], v[52:53], s[60:61] op_sel_hi:[1,0]
	v_pk_add_f32 v[134:135], v[134:135], 1.0 op_sel_hi:[1,0]
	v_exp_f32_e32 v156, v156
	v_exp_f32_e32 v157, v157
	v_rcp_f32_e32 v134, v134
	v_rcp_f32_e32 v135, v135
	v_perm_b32 v133, v144, v133, s46
	v_pk_add_f32 v[156:157], v[156:157], 1.0 op_sel_hi:[1,0]
	v_exp_f32_e32 v159, v159
	v_pk_fma_f32 v[134:135], v[134:135], s[62:63], v[128:129] op_sel_hi:[1,0,0]
	v_rcp_f32_e32 v156, v156
	v_rcp_f32_e32 v157, v157
	v_max_f32_e32 v134, 0x4b000001, v134
	v_max_f32_e32 v135, 0x4b000001, v135
	v_perm_b32 v134, v135, v134, s46
	v_perm_b32 v133, v134, v133, s47
	v_pk_mul_f32 v[134:135], v[54:55], s[60:61] op_sel_hi:[1,0]
	v_pk_fma_f32 v[156:157], v[156:157], s[62:63], v[128:129] op_sel_hi:[1,0,0]
	v_exp_f32_e32 v134, v134
	v_exp_f32_e32 v135, v135
	v_max_f32_e32 v144, 0x4b000001, v156
	v_max_f32_e32 v151, 0x4b000001, v157
	v_pk_mul_f32 v[156:157], v[50:51], s[60:61] op_sel_hi:[1,0]
	v_pk_add_f32 v[134:135], v[134:135], 1.0 op_sel_hi:[1,0]
	v_exp_f32_e32 v156, v156
	v_exp_f32_e32 v157, v157
	v_rcp_f32_e32 v134, v134
	v_rcp_f32_e32 v135, v135
	v_pk_add_f32 v[158:159], v[158:159], 1.0 op_sel_hi:[1,0]
	v_pk_add_f32 v[156:157], v[156:157], 1.0 op_sel_hi:[1,0]
	v_rcp_f32_e32 v158, v158
	v_rcp_f32_e32 v159, v159
	v_rcp_f32_e32 v156, v156
	v_rcp_f32_e32 v157, v157
	v_pk_fma_f32 v[134:135], v[134:135], s[62:63], v[128:129] op_sel_hi:[1,0,0]
	v_perm_b32 v144, v151, v144, s46
	v_max_f32_e32 v134, 0x4b000001, v134
	v_max_f32_e32 v135, 0x4b000001, v135
	v_perm_b32 v134, v135, v134, s46
	v_pk_fma_f32 v[156:157], v[156:157], s[62:63], v[128:129] op_sel_hi:[1,0,0]
	v_pk_fma_f32 v[158:159], v[158:159], s[62:63], v[128:129] op_sel_hi:[1,0,0]
	v_perm_b32 v134, v134, v144, s47
	v_max_f32_e32 v135, 0x4b000001, v158
	v_max_f32_e32 v144, 0x4b000001, v159
	v_max_f32_e32 v151, 0x4b000001, v156
	v_max_f32_e32 v153, 0x4b000001, v157
	s_movk_i32 s4, 0x1000
	v_perm_b32 v135, v144, v135, s46
	v_perm_b32 v144, v153, v151, s46
	v_add_co_u32_e32 v130, vcc, s4, v130
	v_perm_b32 v135, v144, v135, s47
	s_nop 0
	v_addc_co_u32_e32 v131, vcc, 0, v131, vcc
	global_store_dwordx4 v[130:131], v[132:135], off sc1
	v_pk_mul_f32 v[156:157], v[40:41], s[60:61] op_sel_hi:[1,0]
	v_pk_mul_f32 v[158:159], v[32:33], s[60:61] op_sel_hi:[1,0]
	v_pk_mul_f32 v[132:133], v[46:47], s[60:61] op_sel_hi:[1,0]
	v_pk_mul_f32 v[134:135], v[44:45], s[60:61] op_sel_hi:[1,0]
	v_exp_f32_e32 v132, v132
	v_exp_f32_e32 v134, v134
	v_exp_f32_e32 v135, v135
	v_exp_f32_e32 v133, v133
	v_exp_f32_e32 v156, v156
	v_exp_f32_e32 v157, v157
	v_pk_add_f32 v[134:135], v[134:135], 1.0 op_sel_hi:[1,0]
	v_pk_add_f32 v[132:133], v[132:133], 1.0 op_sel_hi:[1,0]
	v_rcp_f32_e32 v134, v134
	v_rcp_f32_e32 v135, v135
	v_rcp_f32_e32 v132, v132
	v_rcp_f32_e32 v133, v133
	v_pk_add_f32 v[156:157], v[156:157], 1.0 op_sel_hi:[1,0]
	v_pk_fma_f32 v[134:135], v[134:135], s[62:63], v[128:129] op_sel_hi:[1,0,0]
	v_rcp_f32_e32 v156, v156
	v_pk_fma_f32 v[132:133], v[132:133], s[62:63], v[128:129] op_sel_hi:[1,0,0]
	v_max_f32_e32 v134, 0x4b000001, v134
	v_max_f32_e32 v135, 0x4b000001, v135
	v_max_f32_e32 v132, 0x4b000001, v132
	v_max_f32_e32 v133, 0x4b000001, v133
	v_perm_b32 v134, v135, v134, s46
	v_perm_b32 v132, v133, v132, s46
	v_rcp_f32_e32 v157, v157
	v_perm_b32 v132, v132, v134, s47
	v_pk_mul_f32 v[134:135], v[42:43], s[60:61] op_sel_hi:[1,0]
	v_exp_f32_e32 v158, v158
	v_exp_f32_e32 v134, v134
	v_exp_f32_e32 v135, v135
	v_pk_fma_f32 v[156:157], v[156:157], s[62:63], v[128:129] op_sel_hi:[1,0,0]
	v_exp_f32_e32 v159, v159
	v_max_f32_e32 v133, 0x4b000001, v156
	v_max_f32_e32 v144, 0x4b000001, v157
	v_pk_mul_f32 v[156:157], v[36:37], s[60:61] op_sel_hi:[1,0]
	v_pk_add_f32 v[134:135], v[134:135], 1.0 op_sel_hi:[1,0]
	v_exp_f32_e32 v156, v156
	v_exp_f32_e32 v157, v157
	v_rcp_f32_e32 v134, v134
	v_rcp_f32_e32 v135, v135
	v_perm_b32 v133, v144, v133, s46
	v_pk_add_f32 v[156:157], v[156:157], 1.0 op_sel_hi:[1,0]
	v_pk_add_f32 v[158:159], v[158:159], 1.0 op_sel_hi:[1,0]
	v_pk_fma_f32 v[134:135], v[134:135], s[62:63], v[128:129] op_sel_hi:[1,0,0]
	v_rcp_f32_e32 v156, v156
	v_rcp_f32_e32 v157, v157
	v_max_f32_e32 v134, 0x4b000001, v134
	v_max_f32_e32 v135, 0x4b000001, v135
	v_perm_b32 v134, v135, v134, s46
	v_perm_b32 v133, v134, v133, s47
	v_pk_mul_f32 v[134:135], v[38:39], s[60:61] op_sel_hi:[1,0]
	v_pk_fma_f32 v[156:157], v[156:157], s[62:63], v[128:129] op_sel_hi:[1,0,0]
	v_exp_f32_e32 v134, v134
	v_exp_f32_e32 v135, v135
	v_max_f32_e32 v144, 0x4b000001, v156
	v_max_f32_e32 v151, 0x4b000001, v157
	v_pk_mul_f32 v[156:157], v[34:35], s[60:61] op_sel_hi:[1,0]
	v_pk_add_f32 v[134:135], v[134:135], 1.0 op_sel_hi:[1,0]
	v_exp_f32_e32 v156, v156
	v_exp_f32_e32 v157, v157
	v_rcp_f32_e32 v134, v134
	v_rcp_f32_e32 v135, v135
	v_rcp_f32_e32 v158, v158
	v_pk_add_f32 v[156:157], v[156:157], 1.0 op_sel_hi:[1,0]
	v_rcp_f32_e32 v159, v159
	v_rcp_f32_e32 v156, v156
	v_rcp_f32_e32 v157, v157
	v_pk_fma_f32 v[134:135], v[134:135], s[62:63], v[128:129] op_sel_hi:[1,0,0]
	v_perm_b32 v144, v151, v144, s46
	v_max_f32_e32 v134, 0x4b000001, v134
	v_max_f32_e32 v135, 0x4b000001, v135
	v_perm_b32 v134, v135, v134, s46
	v_pk_fma_f32 v[156:157], v[156:157], s[62:63], v[128:129] op_sel_hi:[1,0,0]
	v_pk_fma_f32 v[158:159], v[158:159], s[62:63], v[128:129] op_sel_hi:[1,0,0]
	v_perm_b32 v134, v134, v144, s47
	v_max_f32_e32 v135, 0x4b000001, v158
	v_max_f32_e32 v144, 0x4b000001, v159
	v_max_f32_e32 v151, 0x4b000001, v156
	v_max_f32_e32 v153, 0x4b000001, v157
	v_perm_b32 v135, v144, v135, s46
	v_perm_b32 v144, v153, v151, s46
	v_perm_b32 v135, v144, v135, s47
	global_store_dwordx4 v[130:131], v[132:135], off offset:1024 sc1
	v_pk_mul_f32 v[156:157], v[24:25], s[60:61] op_sel_hi:[1,0]
	v_pk_mul_f32 v[158:159], v[16:17], s[60:61] op_sel_hi:[1,0]
	v_pk_mul_f32 v[132:133], v[30:31], s[60:61] op_sel_hi:[1,0]
	v_pk_mul_f32 v[134:135], v[28:29], s[60:61] op_sel_hi:[1,0]
	v_exp_f32_e32 v132, v132
	v_exp_f32_e32 v134, v134
	v_exp_f32_e32 v135, v135
	v_exp_f32_e32 v133, v133
	v_exp_f32_e32 v156, v156
	v_exp_f32_e32 v157, v157
	v_pk_add_f32 v[134:135], v[134:135], 1.0 op_sel_hi:[1,0]
	v_pk_add_f32 v[132:133], v[132:133], 1.0 op_sel_hi:[1,0]
	v_rcp_f32_e32 v134, v134
	v_rcp_f32_e32 v135, v135
	v_rcp_f32_e32 v132, v132
	v_rcp_f32_e32 v133, v133
	v_pk_add_f32 v[156:157], v[156:157], 1.0 op_sel_hi:[1,0]
	v_pk_fma_f32 v[134:135], v[134:135], s[62:63], v[128:129] op_sel_hi:[1,0,0]
	v_rcp_f32_e32 v156, v156
	v_pk_fma_f32 v[132:133], v[132:133], s[62:63], v[128:129] op_sel_hi:[1,0,0]
	v_max_f32_e32 v134, 0x4b000001, v134
	v_max_f32_e32 v135, 0x4b000001, v135
	v_max_f32_e32 v132, 0x4b000001, v132
	v_max_f32_e32 v133, 0x4b000001, v133
	v_perm_b32 v134, v135, v134, s46
	v_perm_b32 v132, v133, v132, s46
	v_rcp_f32_e32 v157, v157
	v_perm_b32 v132, v132, v134, s47
	v_pk_mul_f32 v[134:135], v[26:27], s[60:61] op_sel_hi:[1,0]
	v_exp_f32_e32 v158, v158
	v_exp_f32_e32 v134, v134
	v_exp_f32_e32 v135, v135
	v_pk_fma_f32 v[156:157], v[156:157], s[62:63], v[128:129] op_sel_hi:[1,0,0]
	v_exp_f32_e32 v159, v159
	v_max_f32_e32 v133, 0x4b000001, v156
	v_max_f32_e32 v144, 0x4b000001, v157
	v_pk_mul_f32 v[156:157], v[20:21], s[60:61] op_sel_hi:[1,0]
	v_pk_add_f32 v[134:135], v[134:135], 1.0 op_sel_hi:[1,0]
	v_exp_f32_e32 v156, v156
	v_exp_f32_e32 v157, v157
	v_rcp_f32_e32 v134, v134
	v_rcp_f32_e32 v135, v135
	v_perm_b32 v133, v144, v133, s46
	v_pk_add_f32 v[156:157], v[156:157], 1.0 op_sel_hi:[1,0]
	v_pk_add_f32 v[158:159], v[158:159], 1.0 op_sel_hi:[1,0]
	v_pk_fma_f32 v[134:135], v[134:135], s[62:63], v[128:129] op_sel_hi:[1,0,0]
	v_rcp_f32_e32 v156, v156
	v_rcp_f32_e32 v157, v157
	v_max_f32_e32 v134, 0x4b000001, v134
	v_max_f32_e32 v135, 0x4b000001, v135
	v_perm_b32 v134, v135, v134, s46
	v_perm_b32 v133, v134, v133, s47
	v_pk_mul_f32 v[134:135], v[22:23], s[60:61] op_sel_hi:[1,0]
	v_pk_fma_f32 v[156:157], v[156:157], s[62:63], v[128:129] op_sel_hi:[1,0,0]
	v_exp_f32_e32 v134, v134
	v_exp_f32_e32 v135, v135
	v_max_f32_e32 v144, 0x4b000001, v156
	v_max_f32_e32 v151, 0x4b000001, v157
	v_pk_mul_f32 v[156:157], v[18:19], s[60:61] op_sel_hi:[1,0]
	v_pk_add_f32 v[134:135], v[134:135], 1.0 op_sel_hi:[1,0]
	v_exp_f32_e32 v156, v156
	v_exp_f32_e32 v157, v157
	v_rcp_f32_e32 v134, v134
	v_rcp_f32_e32 v135, v135
	v_rcp_f32_e32 v158, v158
	v_pk_add_f32 v[156:157], v[156:157], 1.0 op_sel_hi:[1,0]
	v_rcp_f32_e32 v159, v159
	v_rcp_f32_e32 v156, v156
	v_rcp_f32_e32 v157, v157
	v_pk_fma_f32 v[134:135], v[134:135], s[62:63], v[128:129] op_sel_hi:[1,0,0]
	v_perm_b32 v144, v151, v144, s46
	v_max_f32_e32 v134, 0x4b000001, v134
	v_max_f32_e32 v135, 0x4b000001, v135
	v_perm_b32 v134, v135, v134, s46
	v_pk_fma_f32 v[156:157], v[156:157], s[62:63], v[128:129] op_sel_hi:[1,0,0]
	v_pk_fma_f32 v[158:159], v[158:159], s[62:63], v[128:129] op_sel_hi:[1,0,0]
	v_perm_b32 v134, v134, v144, s47
	v_max_f32_e32 v135, 0x4b000001, v158
	v_max_f32_e32 v144, 0x4b000001, v159
	v_max_f32_e32 v151, 0x4b000001, v156
	v_max_f32_e32 v153, 0x4b000001, v157
	v_perm_b32 v135, v144, v135, s46
	v_perm_b32 v144, v153, v151, s46
	v_perm_b32 v135, v144, v135, s47
	global_store_dwordx4 v[130:131], v[132:135], off offset:2048 sc1
	v_pk_mul_f32 v[156:157], v[8:9], s[60:61] op_sel_hi:[1,0]
	v_pk_mul_f32 v[158:159], v[0:1], s[60:61] op_sel_hi:[1,0]
	v_pk_mul_f32 v[132:133], v[14:15], s[60:61] op_sel_hi:[1,0]
	v_pk_mul_f32 v[134:135], v[12:13], s[60:61] op_sel_hi:[1,0]
	v_exp_f32_e32 v132, v132
	v_exp_f32_e32 v134, v134
	v_exp_f32_e32 v135, v135
	v_exp_f32_e32 v133, v133
	v_exp_f32_e32 v156, v156
	v_exp_f32_e32 v157, v157
	v_pk_add_f32 v[134:135], v[134:135], 1.0 op_sel_hi:[1,0]
	v_pk_add_f32 v[132:133], v[132:133], 1.0 op_sel_hi:[1,0]
	v_rcp_f32_e32 v134, v134
	v_rcp_f32_e32 v135, v135
	v_rcp_f32_e32 v132, v132
	v_rcp_f32_e32 v133, v133
	v_pk_add_f32 v[156:157], v[156:157], 1.0 op_sel_hi:[1,0]
	v_pk_fma_f32 v[134:135], v[134:135], s[62:63], v[128:129] op_sel_hi:[1,0,0]
	v_rcp_f32_e32 v156, v156
	v_pk_fma_f32 v[132:133], v[132:133], s[62:63], v[128:129] op_sel_hi:[1,0,0]
	v_max_f32_e32 v134, 0x4b000001, v134
	v_max_f32_e32 v135, 0x4b000001, v135
	v_max_f32_e32 v132, 0x4b000001, v132
	v_max_f32_e32 v133, 0x4b000001, v133
	v_perm_b32 v134, v135, v134, s46
	v_perm_b32 v132, v133, v132, s46
	v_rcp_f32_e32 v157, v157
	v_perm_b32 v132, v132, v134, s47
	v_pk_mul_f32 v[134:135], v[10:11], s[60:61] op_sel_hi:[1,0]
	v_exp_f32_e32 v158, v158
	v_exp_f32_e32 v134, v134
	v_exp_f32_e32 v135, v135
	v_pk_fma_f32 v[156:157], v[156:157], s[62:63], v[128:129] op_sel_hi:[1,0,0]
	v_exp_f32_e32 v159, v159
	v_max_f32_e32 v133, 0x4b000001, v156
	v_max_f32_e32 v144, 0x4b000001, v157
	v_pk_mul_f32 v[156:157], v[4:5], s[60:61] op_sel_hi:[1,0]
	v_pk_add_f32 v[134:135], v[134:135], 1.0 op_sel_hi:[1,0]
	v_exp_f32_e32 v156, v156
	v_exp_f32_e32 v157, v157
	v_rcp_f32_e32 v134, v134
	v_rcp_f32_e32 v135, v135
	v_perm_b32 v133, v144, v133, s46
	v_pk_add_f32 v[156:157], v[156:157], 1.0 op_sel_hi:[1,0]
	v_pk_add_f32 v[158:159], v[158:159], 1.0 op_sel_hi:[1,0]
	v_pk_fma_f32 v[134:135], v[134:135], s[62:63], v[128:129] op_sel_hi:[1,0,0]
	v_rcp_f32_e32 v156, v156
	v_rcp_f32_e32 v157, v157
	v_max_f32_e32 v134, 0x4b000001, v134
	v_max_f32_e32 v135, 0x4b000001, v135
	v_perm_b32 v134, v135, v134, s46
	v_perm_b32 v133, v134, v133, s47
	v_pk_mul_f32 v[134:135], v[6:7], s[60:61] op_sel_hi:[1,0]
	v_pk_fma_f32 v[156:157], v[156:157], s[62:63], v[128:129] op_sel_hi:[1,0,0]
	v_exp_f32_e32 v134, v134
	v_exp_f32_e32 v135, v135
	v_max_f32_e32 v144, 0x4b000001, v156
	v_max_f32_e32 v151, 0x4b000001, v157
	v_pk_mul_f32 v[156:157], v[2:3], s[60:61] op_sel_hi:[1,0]
	v_pk_add_f32 v[134:135], v[134:135], 1.0 op_sel_hi:[1,0]
	v_exp_f32_e32 v156, v156
	v_exp_f32_e32 v157, v157
	v_rcp_f32_e32 v134, v134
	v_rcp_f32_e32 v135, v135
	v_rcp_f32_e32 v158, v158
	v_pk_add_f32 v[156:157], v[156:157], 1.0 op_sel_hi:[1,0]
	v_rcp_f32_e32 v159, v159
	v_rcp_f32_e32 v156, v156
	v_rcp_f32_e32 v157, v157
	v_pk_fma_f32 v[134:135], v[134:135], s[62:63], v[128:129] op_sel_hi:[1,0,0]
	v_perm_b32 v144, v151, v144, s46
	v_max_f32_e32 v134, 0x4b000001, v134
	v_max_f32_e32 v135, 0x4b000001, v135
	v_perm_b32 v134, v135, v134, s46
	v_pk_fma_f32 v[156:157], v[156:157], s[62:63], v[128:129] op_sel_hi:[1,0,0]
	v_pk_fma_f32 v[128:129], v[158:159], s[62:63], v[128:129] op_sel_hi:[1,0,0]
	v_perm_b32 v134, v134, v144, s47
	v_max_f32_e32 v128, 0x4b000001, v128
	v_max_f32_e32 v129, 0x4b000001, v129
	v_max_f32_e32 v135, 0x4b000001, v156
	v_max_f32_e32 v144, 0x4b000001, v157
	v_perm_b32 v128, v129, v128, s46
	v_perm_b32 v129, v144, v135, s46
	v_perm_b32 v135, v129, v128, s47
	global_store_dwordx4 v[130:131], v[132:135], off offset:3072 sc1
	s_waitcnt vmcnt(8)
